# even XCDs run P7 tile by tile (PP t0, gate t0, PP t1, gate t1) so their output-epilogue bursts interleave with the odd XCDs
# speedup vs baseline: 1.0018x; 1.0018x over previous
.LBB0_978:
	s_cmp_lg_u32 s27, 7
	s_cselect_b64 s[0:1], -1, 0
	s_and_b64 s[0:1], s[54:55], s[0:1]
	s_and_b64 vcc, exec, s[0:1]
	s_cbranch_vccnz .LBB0_1031
	s_bitcmp1_b32 s99, 0
	s_cbranch_scc0 .Lil_skip
	s_bitcmp1_b32 s99, 4
	s_cbranch_scc1 .Lil_skip
	v_writelane_b32 v255, s33, 40
	v_writelane_b32 v255, s76, 41
	v_writelane_b32 v255, s2, 42
	s_or_b32 s99, s99, 0x40
	s_movk_i32 s3, 0x200
.Lil_skip:
.Lpp_entry:
	v_mov_b32_e32 v0, 0
	s_add_u32 s4, s76, 0x16c00000
	v_mbcnt_lo_u32_b32 v0, -1, v0
	s_addc_u32 s5, s77, 0
	v_mbcnt_hi_u32_b32 v0, -1, v0
	s_waitcnt vmcnt(19)
	v_add_u32_e32 v8, s33, v0
	s_cmpk_lt_i32 s2, 0x200
	v_mov_b32_e32 v142, 0
	s_cselect_b64 s[6:7], -1, 0
	s_cmpk_gt_i32 s2, 0x1ff
	v_readfirstlane_b32 s14, v8
	s_cbranch_scc1 .LBB0_1001
	s_bitcmp1_b32 s99, 5
	s_cbranch_scc1 .Lpp_noskip
	s_bitcmp1_b32 s99, 4
	s_cbranch_scc1 .LBB0_1001

.LBB0_1030:
	s_waitcnt vmcnt(0)
	s_barrier
	s_bitcmp1_b32 s99, 6
	s_cbranch_scc0 .LBB0_1031
	s_bitcmp1_b32 s99, 7
	s_cbranch_scc1 .LBB0_1031
	s_or_b32 s99, s99, 0x80
	v_readlane_b32 s33, v255, 40
	v_readlane_b32 s76, v255, 41
	v_readlane_b32 s2, v255, 42
	s_nop 1
	s_addk_i32 s2, 0x100
	s_branch .Lpp_entry
